# v86 (v36 edits + 64-bit accumulator zeroing) + back-edge rotation of the 8 K-loops
# baseline (speedup 1.0000x reference)
; #define PG8_STAGE(bufoff, gbase, voff) do { _Pragma("unroll") for (int _i = 0; _i < 2; ++_i) { unsigned keep_; \
;         asm volatile("s_mov_b32 %0, m0\n\ts_mov_b32 m0, %3\n\ts_nop 0\n\tglobal_load_lds_dwordx4 %1, %2\n\ts_mov_b32 m0, %0" \
;             : "=&s"(keep_) : "v"((voff)[_i]), "s"((const void*)(gbase)), "s"(ldsb0 + (unsigned)(bufoff) + (unsigned)(_i * 8192)) : "memory"); } } while (0)
; #define PG8_LDA(dst, b, h) do { _Pragma("unroll") for (int m = 0; m < 4; ++m) _Pragma("unroll") for (int k = 0; k < 2; ++k) dst[m][k] = *(const LAS bf16x8*)(lds + PG8_SA(b, h) + aoff + m * 2048 + k * 1024); } while (0)
; #define PG8_LDB(dst, b, h) do { _Pragma("unroll") for (int n = 0; n < 2; ++n) _Pragma("unroll") for (int k = 0; k < 2; ++k) dst[n][k] = *(const LAS bf16x8*)(lds + PG8_SB(b, h) + boff + n * 2048 + k * 1024); } while (0)
; #define PG8_MMA(ai, bj, At, Bt) do { __builtin_amdgcn_s_setprio(1); _Pragma("unroll") for (int m = 0; m < 4; ++m) _Pragma("unroll") for (int n = 0; n < 2; ++n) _Pragma("unroll") for (int k = 0; k < 2; ++k) \
;         acc[ai][bj][m][n] = __builtin_amdgcn_mfma_f32_16x16x32_bf16(Bt[n][k], At[m][k], acc[ai][bj][m][n], 0, 0, 0); __builtin_amdgcn_s_setprio(0); } while (0)
; #define PG8_WAIT_V(n) asm volatile("s_waitcnt vmcnt(" #n ")" ::: "memory")
; #define PG8_BAR __builtin_amdgcn_s_barrier()
; template <class Epi, class Sched, bool ALIGN_EPI>
; __device__ __forceinline__ void gemm_phase(LAS unsigned char* lds, const Gemm g, const Sched& S, const Epi& E) {
;     ...
;         for (int t = 0; t < nt; t += 2) {
;             const bool last = (t == nt - 2);
;             const char* a1 = cA + (size_t)(t + 1) * kstep;
;             const char* a2 = last ? nA : cA + (size_t)(t + 2) * kstep; const char* b2 = last ? nB : cB + (size_t)(t + 2) * kstep;
;             const char* a3 = a2 + kstep; const char* b3 = b2 + kstep;
;             PG8_LDB(B0, 0, 0); PG8_LDB(B1, 0, 1); PG8_SCHED; PG8_LDA(At, 0, 0); PG8_STAGE(PG8_SA(1, 1), a1 + hstepA, voffA);
;             PG8_WAIT_V(8); PG8_WAIT_L(0); PG8_BAR; PG8_MMA(0, 0, At, B0); PG8_MMA(0, 1, At, B1); PG8_BAR; PG8_SCHED;
;             PG8_LDA(At, 0, 1); PG8_STAGE(PG8_SB(0, 0), b2, voffB); PG8_STAGE(PG8_SB(0, 1), b2 + hstepB, voffB); PG8_STAGE(PG8_SA(0, 0), a2, voffA);
;             PG8_WAIT_V(8); PG8_WAIT_L(0); PG8_BAR; PG8_MMA(1, 0, At, B0); PG8_MMA(1, 1, At, B1); PG8_BAR; PG8_SCHED;
.LBB0_2172:
	s_add_u32 s61, s22, s26
	s_addc_u32 s63, s23, s27
	s_add_u32 s28, s61, 0x100
	v_add_u32_e32 v141, 0x10000, v139
	s_addc_u32 s29, s63, 0
	ds_read_b128 v[142:145], v141
	ds_read_b128 v[146:149], v141 offset:1024
	ds_read_b128 v[150:153], v141 offset:2048
	ds_read_b128 v[154:157], v141 offset:3072
	v_add_u32_e32 v141, 0x14000, v139
	s_add_u32 s30, s20, s26
	ds_read_b128 v[158:161], v141
	ds_read_b128 v[162:165], v141 offset:1024
	ds_read_b128 v[166:169], v141 offset:2048
	ds_read_b128 v[170:173], v141 offset:3072
	s_addc_u32 s31, s21, s27
	s_add_u32 s30, s30, 0x100
	s_addc_u32 s31, s31, 0
	s_cmpk_eq_i32 s60, 0x54
	s_cselect_b32 s34, s12, s28
	s_cselect_b32 s35, s13, s29
	s_cselect_b32 s30, s24, s30
	s_cselect_b32 s31, s25, s31
	s_add_u32 s28, s34, 0x80
	s_addc_u32 s29, s35, 0
	ds_read_b128 v[174:177], v140
	ds_read_b128 v[178:181], v140 offset:1024
	ds_read_b128 v[182:185], v140 offset:2048
	ds_read_b128 v[186:189], v140 offset:3072
	ds_read_b128 v[190:193], v140 offset:4096
	ds_read_b128 v[194:197], v140 offset:5120
	ds_read_b128 v[198:201], v140 offset:6144
	ds_read_b128 v[204:207], v140 offset:7168
	s_add_u32 s62, s61, 0x160080
	s_addc_u32 s63, s63, 0
	s_mov_b32 m0, s54
	s_nop 0
	global_load_lds_dwordx4 v131, s[62:63]
	s_nop 0
	s_mov_b32 m0, s55
	s_nop 0
	global_load_lds_dwordx4 v137, s[62:63]
	s_waitcnt vmcnt(8)
	s_waitcnt lgkmcnt(0)
	s_barrier
	s_setprio 1
	v_mfma_f32_16x16x32_bf16 v[126:129], v[142:145], v[174:177], v[126:129]
	v_mfma_f32_16x16x32_bf16 v[122:125], v[150:153], v[174:177], v[122:125]
	v_mfma_f32_16x16x32_bf16 v[110:113], v[142:145], v[182:185], v[110:113]
	v_mfma_f32_16x16x32_bf16 v[106:109], v[150:153], v[182:185], v[106:109]
	v_mfma_f32_16x16x32_bf16 v[94:97], v[142:145], v[190:193], v[94:97]
	v_mfma_f32_16x16x32_bf16 v[90:93], v[150:153], v[190:193], v[90:93]
	v_mfma_f32_16x16x32_bf16 v[78:81], v[142:145], v[198:201], v[78:81]
	v_mfma_f32_16x16x32_bf16 v[74:77], v[150:153], v[198:201], v[74:77]
	v_mfma_f32_16x16x32_bf16 v[126:129], v[146:149], v[178:181], v[126:129]
	v_mfma_f32_16x16x32_bf16 v[122:125], v[154:157], v[178:181], v[122:125]
	v_mfma_f32_16x16x32_bf16 v[110:113], v[146:149], v[186:189], v[110:113]
	v_mfma_f32_16x16x32_bf16 v[106:109], v[154:157], v[186:189], v[106:109]
	v_mfma_f32_16x16x32_bf16 v[94:97], v[146:149], v[194:197], v[94:97]
	v_mfma_f32_16x16x32_bf16 v[90:93], v[154:157], v[194:197], v[90:93]
	v_mfma_f32_16x16x32_bf16 v[78:81], v[146:149], v[204:207], v[78:81]
	v_mfma_f32_16x16x32_bf16 v[74:77], v[154:157], v[204:207], v[74:77]
	v_mfma_f32_16x16x32_bf16 v[118:121], v[158:161], v[174:177], v[118:121]
	v_mfma_f32_16x16x32_bf16 v[114:117], v[166:169], v[174:177], v[114:117]
	v_mfma_f32_16x16x32_bf16 v[102:105], v[158:161], v[182:185], v[102:105]
	v_mfma_f32_16x16x32_bf16 v[98:101], v[166:169], v[182:185], v[98:101]
	v_mfma_f32_16x16x32_bf16 v[86:89], v[158:161], v[190:193], v[86:89]
	v_mfma_f32_16x16x32_bf16 v[82:85], v[166:169], v[190:193], v[82:85]
	v_mfma_f32_16x16x32_bf16 v[70:73], v[158:161], v[198:201], v[70:73]
	v_mfma_f32_16x16x32_bf16 v[66:69], v[166:169], v[198:201], v[66:69]
	v_mfma_f32_16x16x32_bf16 v[118:121], v[162:165], v[178:181], v[118:121]
	v_mfma_f32_16x16x32_bf16 v[114:117], v[170:173], v[178:181], v[114:117]
	v_mfma_f32_16x16x32_bf16 v[102:105], v[162:165], v[186:189], v[102:105]
	v_mfma_f32_16x16x32_bf16 v[98:101], v[170:173], v[186:189], v[98:101]
	v_mfma_f32_16x16x32_bf16 v[86:89], v[162:165], v[194:197], v[86:89]
	v_mfma_f32_16x16x32_bf16 v[82:85], v[170:173], v[194:197], v[82:85]
	v_mfma_f32_16x16x32_bf16 v[70:73], v[162:165], v[204:207], v[70:73]
	v_mfma_f32_16x16x32_bf16 v[66:69], v[170:173], v[204:207], v[66:69]
	s_setprio 0
	s_barrier
	ds_read_b128 v[174:177], v140 offset:16384
	ds_read_b128 v[178:181], v140 offset:17408
	ds_read_b128 v[182:185], v140 offset:18432
	ds_read_b128 v[186:189], v140 offset:19456
	ds_read_b128 v[190:193], v140 offset:20480
	ds_read_b128 v[194:197], v140 offset:21504
	ds_read_b128 v[198:201], v140 offset:22528
	ds_read_b128 v[204:207], v140 offset:23552
	s_mov_b32 m0, s3
	s_nop 0
	global_load_lds_dwordx4 v136, s[30:31]
	s_add_u32 s62, s30, 0x160000
	s_mov_b32 m0, s41
	s_nop 0
	global_load_lds_dwordx4 v138, s[30:31]
	s_addc_u32 s63, s31, 0
	s_mov_b32 m0, s42
	s_nop 0
	global_load_lds_dwordx4 v136, s[62:63]
	s_nop 0
	s_mov_b32 m0, s43
	s_nop 0
	global_load_lds_dwordx4 v138, s[62:63]
	s_nop 0
	s_mov_b32 m0, s2
	s_nop 0
	global_load_lds_dwordx4 v131, s[34:35]
	s_nop 0
	s_mov_b32 m0, s44
	s_nop 0
	global_load_lds_dwordx4 v137, s[34:35]
	s_waitcnt vmcnt(8)
	s_waitcnt lgkmcnt(0)
	s_barrier
; #define PG8_STAGE(bufoff, gbase, voff) do { _Pragma("unroll") for (int _i = 0; _i < 2; ++_i) { unsigned keep_; \
;         asm volatile("s_mov_b32 %0, m0\n\ts_mov_b32 m0, %3\n\ts_nop 0\n\tglobal_load_lds_dwordx4 %1, %2\n\ts_mov_b32 m0, %0" \
;             : "=&s"(keep_) : "v"((voff)[_i]), "s"((const void*)(gbase)), "s"(ldsb0 + (unsigned)(bufoff) + (unsigned)(_i * 8192)) : "memory"); } } while (0)
; #define PG8_LDA(dst, b, h) do { _Pragma("unroll") for (int m = 0; m < 4; ++m) _Pragma("unroll") for (int k = 0; k < 2; ++k) dst[m][k] = *(const LAS bf16x8*)(lds + PG8_SA(b, h) + aoff + m * 2048 + k * 1024); } while (0)
; #define PG8_LDB(dst, b, h) do { _Pragma("unroll") for (int n = 0; n < 2; ++n) _Pragma("unroll") for (int k = 0; k < 2; ++k) dst[n][k] = *(const LAS bf16x8*)(lds + PG8_SB(b, h) + boff + n * 2048 + k * 1024); } while (0)
; #define PG8_MMA(ai, bj, At, Bt) do { __builtin_amdgcn_s_setprio(1); _Pragma("unroll") for (int m = 0; m < 4; ++m) _Pragma("unroll") for (int n = 0; n < 2; ++n) _Pragma("unroll") for (int k = 0; k < 2; ++k) \
;         acc[ai][bj][m][n] = __builtin_amdgcn_mfma_f32_16x16x32_bf16(Bt[n][k], At[m][k], acc[ai][bj][m][n], 0, 0, 0); __builtin_amdgcn_s_setprio(0); } while (0)
; #define PG8_WAIT_V(n) asm volatile("s_waitcnt vmcnt(" #n ")" ::: "memory")
; #define PG8_WAIT_L(n) asm volatile("s_waitcnt lgkmcnt(" #n ")" ::: "memory")
; #define PG8_BAR __builtin_amdgcn_s_barrier()
; #define PG8_SCHED __builtin_amdgcn_sched_barrier(0)
; template <class Epi, class Sched, bool ALIGN_EPI>
; __device__ __forceinline__ void gemm_phase(LAS unsigned char* lds, const Gemm g, const Sched& S, const Epi& E) {
;     ...
;             PG8_WAIT_V(8); PG8_WAIT_L(0); PG8_BAR; PG8_MMA(1, 0, At, B0); PG8_MMA(1, 1, At, B1); PG8_BAR; PG8_SCHED;
;             PG8_LDB(B0, 1, 0); PG8_LDB(B1, 1, 1); PG8_SCHED; PG8_LDA(At, 1, 0); PG8_STAGE(PG8_SA(0, 1), a2 + hstepA, voffA);
;             PG8_WAIT_V(8); PG8_WAIT_L(0); PG8_BAR; PG8_MMA(0, 0, At, B0); PG8_MMA(0, 1, At, B1); PG8_BAR; PG8_SCHED;
	s_setprio 1
	v_mfma_f32_16x16x32_bf16 v[62:65], v[142:145], v[174:177], v[62:65]
	v_mfma_f32_16x16x32_bf16 v[58:61], v[150:153], v[174:177], v[58:61]
	v_mfma_f32_16x16x32_bf16 v[46:49], v[142:145], v[182:185], v[46:49]
	v_mfma_f32_16x16x32_bf16 v[42:45], v[150:153], v[182:185], v[42:45]
	v_mfma_f32_16x16x32_bf16 v[30:33], v[142:145], v[190:193], v[30:33]
	v_mfma_f32_16x16x32_bf16 v[26:29], v[150:153], v[190:193], v[26:29]
	v_mfma_f32_16x16x32_bf16 v[14:17], v[142:145], v[198:201], v[14:17]
	v_mfma_f32_16x16x32_bf16 v[10:13], v[150:153], v[198:201], v[10:13]
	v_mfma_f32_16x16x32_bf16 v[62:65], v[146:149], v[178:181], v[62:65]
	v_mfma_f32_16x16x32_bf16 v[58:61], v[154:157], v[178:181], v[58:61]
	v_mfma_f32_16x16x32_bf16 v[46:49], v[146:149], v[186:189], v[46:49]
	v_mfma_f32_16x16x32_bf16 v[42:45], v[154:157], v[186:189], v[42:45]
	v_mfma_f32_16x16x32_bf16 v[30:33], v[146:149], v[194:197], v[30:33]
	v_mfma_f32_16x16x32_bf16 v[26:29], v[154:157], v[194:197], v[26:29]
	v_mfma_f32_16x16x32_bf16 v[14:17], v[146:149], v[204:207], v[14:17]
	v_mfma_f32_16x16x32_bf16 v[10:13], v[154:157], v[204:207], v[10:13]
	v_mfma_f32_16x16x32_bf16 v[54:57], v[158:161], v[174:177], v[54:57]
	v_mfma_f32_16x16x32_bf16 v[50:53], v[166:169], v[174:177], v[50:53]
	v_mfma_f32_16x16x32_bf16 v[38:41], v[158:161], v[182:185], v[38:41]
	v_mfma_f32_16x16x32_bf16 v[34:37], v[166:169], v[182:185], v[34:37]
	v_mfma_f32_16x16x32_bf16 v[22:25], v[158:161], v[190:193], v[22:25]
	v_mfma_f32_16x16x32_bf16 v[18:21], v[166:169], v[190:193], v[18:21]
	v_mfma_f32_16x16x32_bf16 v[6:9], v[158:161], v[198:201], v[6:9]
	v_mfma_f32_16x16x32_bf16 v[2:5], v[166:169], v[198:201], v[2:5]
	v_mfma_f32_16x16x32_bf16 v[54:57], v[162:165], v[178:181], v[54:57]
	v_mfma_f32_16x16x32_bf16 v[50:53], v[170:173], v[178:181], v[50:53]
	v_mfma_f32_16x16x32_bf16 v[38:41], v[162:165], v[186:189], v[38:41]
	v_mfma_f32_16x16x32_bf16 v[34:37], v[170:173], v[186:189], v[34:37]
	v_mfma_f32_16x16x32_bf16 v[22:25], v[162:165], v[194:197], v[22:25]
	v_mfma_f32_16x16x32_bf16 v[18:21], v[170:173], v[194:197], v[18:21]
	v_mfma_f32_16x16x32_bf16 v[6:9], v[162:165], v[204:207], v[6:9]
	v_mfma_f32_16x16x32_bf16 v[2:5], v[170:173], v[204:207], v[2:5]
	s_setprio 0
	s_barrier
	v_add_u32_e32 v141, 0x18000, v139
	ds_read_b128 v[142:145], v141
	ds_read_b128 v[146:149], v141 offset:1024
	ds_read_b128 v[150:153], v141 offset:2048
	ds_read_b128 v[154:157], v141 offset:3072
	v_add_u32_e32 v141, 0x1c000, v139
	ds_read_b128 v[158:161], v141
	ds_read_b128 v[162:165], v141 offset:1024
	ds_read_b128 v[166:169], v141 offset:2048
	ds_read_b128 v[170:173], v141 offset:3072
	ds_read_b128 v[174:177], v140 offset:32768
	ds_read_b128 v[178:181], v140 offset:33792
	ds_read_b128 v[182:185], v140 offset:34816
	ds_read_b128 v[186:189], v140 offset:35840
	ds_read_b128 v[190:193], v140 offset:36864
	ds_read_b128 v[194:197], v140 offset:37888
	ds_read_b128 v[198:201], v140 offset:38912
	ds_read_b128 v[204:207], v140 offset:39936
	s_add_u32 s34, s34, 0x160000
	s_addc_u32 s35, s35, 0
	s_mov_b32 m0, s46
	s_nop 0
	global_load_lds_dwordx4 v131, s[34:35]
	s_nop 0
	s_mov_b32 m0, s47
	s_nop 0
	global_load_lds_dwordx4 v137, s[34:35]
	s_waitcnt vmcnt(8)
	s_waitcnt lgkmcnt(0)
	s_barrier
	s_setprio 1
	v_mfma_f32_16x16x32_bf16 v[126:129], v[142:145], v[174:177], v[126:129]
	v_mfma_f32_16x16x32_bf16 v[122:125], v[150:153], v[174:177], v[122:125]
	v_mfma_f32_16x16x32_bf16 v[110:113], v[142:145], v[182:185], v[110:113]
	v_mfma_f32_16x16x32_bf16 v[106:109], v[150:153], v[182:185], v[106:109]
	v_mfma_f32_16x16x32_bf16 v[94:97], v[142:145], v[190:193], v[94:97]
	v_mfma_f32_16x16x32_bf16 v[90:93], v[150:153], v[190:193], v[90:93]
	v_mfma_f32_16x16x32_bf16 v[78:81], v[142:145], v[198:201], v[78:81]
	v_mfma_f32_16x16x32_bf16 v[74:77], v[150:153], v[198:201], v[74:77]
	v_mfma_f32_16x16x32_bf16 v[126:129], v[146:149], v[178:181], v[126:129]
	v_mfma_f32_16x16x32_bf16 v[122:125], v[154:157], v[178:181], v[122:125]
	v_mfma_f32_16x16x32_bf16 v[110:113], v[146:149], v[186:189], v[110:113]
	v_mfma_f32_16x16x32_bf16 v[106:109], v[154:157], v[186:189], v[106:109]
	v_mfma_f32_16x16x32_bf16 v[94:97], v[146:149], v[194:197], v[94:97]
	v_mfma_f32_16x16x32_bf16 v[90:93], v[154:157], v[194:197], v[90:93]
	v_mfma_f32_16x16x32_bf16 v[78:81], v[146:149], v[204:207], v[78:81]
	v_mfma_f32_16x16x32_bf16 v[74:77], v[154:157], v[204:207], v[74:77]
	v_mfma_f32_16x16x32_bf16 v[118:121], v[158:161], v[174:177], v[118:121]
	v_mfma_f32_16x16x32_bf16 v[114:117], v[166:169], v[174:177], v[114:117]
	v_mfma_f32_16x16x32_bf16 v[102:105], v[158:161], v[182:185], v[102:105]
	v_mfma_f32_16x16x32_bf16 v[98:101], v[166:169], v[182:185], v[98:101]
	v_mfma_f32_16x16x32_bf16 v[86:89], v[158:161], v[190:193], v[86:89]
	v_mfma_f32_16x16x32_bf16 v[82:85], v[166:169], v[190:193], v[82:85]
	v_mfma_f32_16x16x32_bf16 v[70:73], v[158:161], v[198:201], v[70:73]
	v_mfma_f32_16x16x32_bf16 v[66:69], v[166:169], v[198:201], v[66:69]
	v_mfma_f32_16x16x32_bf16 v[118:121], v[162:165], v[178:181], v[118:121]
	v_mfma_f32_16x16x32_bf16 v[114:117], v[170:173], v[178:181], v[114:117]
	v_mfma_f32_16x16x32_bf16 v[102:105], v[162:165], v[186:189], v[102:105]
	v_mfma_f32_16x16x32_bf16 v[98:101], v[170:173], v[186:189], v[98:101]
	v_mfma_f32_16x16x32_bf16 v[86:89], v[162:165], v[194:197], v[86:89]
	v_mfma_f32_16x16x32_bf16 v[82:85], v[170:173], v[194:197], v[82:85]
	v_mfma_f32_16x16x32_bf16 v[70:73], v[162:165], v[204:207], v[70:73]
	v_mfma_f32_16x16x32_bf16 v[66:69], v[170:173], v[204:207], v[66:69]
	s_setprio 0
	s_barrier
; #define PG8_STAGE(bufoff, gbase, voff) do { _Pragma("unroll") for (int _i = 0; _i < 2; ++_i) { unsigned keep_; \
;         asm volatile("s_mov_b32 %0, m0\n\ts_mov_b32 m0, %3\n\ts_nop 0\n\tglobal_load_lds_dwordx4 %1, %2\n\ts_mov_b32 m0, %0" \
;             : "=&s"(keep_) : "v"((voff)[_i]), "s"((const void*)(gbase)), "s"(ldsb0 + (unsigned)(bufoff) + (unsigned)(_i * 8192)) : "memory"); } } while (0)
; #define PG8_LDA(dst, b, h) do { _Pragma("unroll") for (int m = 0; m < 4; ++m) _Pragma("unroll") for (int k = 0; k < 2; ++k) dst[m][k] = *(const LAS bf16x8*)(lds + PG8_SA(b, h) + aoff + m * 2048 + k * 1024); } while (0)
; #define PG8_MMA(ai, bj, At, Bt) do { __builtin_amdgcn_s_setprio(1); _Pragma("unroll") for (int m = 0; m < 4; ++m) _Pragma("unroll") for (int n = 0; n < 2; ++n) _Pragma("unroll") for (int k = 0; k < 2; ++k) \
;         acc[ai][bj][m][n] = __builtin_amdgcn_mfma_f32_16x16x32_bf16(Bt[n][k], At[m][k], acc[ai][bj][m][n], 0, 0, 0); __builtin_amdgcn_s_setprio(0); } while (0)
; #define PG8_WAIT_V(n) asm volatile("s_waitcnt vmcnt(" #n ")" ::: "memory")
; #define PG8_WAIT_L(n) asm volatile("s_waitcnt lgkmcnt(" #n ")" ::: "memory")
; #define PG8_BAR __builtin_amdgcn_s_barrier()
; #define PG8_SCHED __builtin_amdgcn_sched_barrier(0)
; template <class Epi, class Sched, bool ALIGN_EPI>
; __device__ __forceinline__ void gemm_phase(LAS unsigned char* lds, const Gemm g, const Sched& S, const Epi& E) {
;     ...
;             PG8_LDA(At, 1, 1); PG8_STAGE(PG8_SB(1, 0), b3, voffB); PG8_STAGE(PG8_SB(1, 1), b3 + hstepB, voffB); PG8_STAGE(PG8_SA(1, 0), a3, voffA);
;             PG8_WAIT_V(8); PG8_WAIT_L(0); PG8_BAR; PG8_MMA(1, 0, At, B0); PG8_MMA(1, 1, At, B1); PG8_BAR; PG8_SCHED;
;         }
;         if constexpr (ALIGN_EPI) { if (wr == 0) PG8_BAR; }
;         if constexpr (Epi::NPRE > 0) E(acc, cur, wr, wc, fr, fq, pre); else
;         if constexpr (!Epi::AFTER_DRAIN) E(acc, cur, wr, wc, fr, fq);
;         if (!has_next) break;
; #pragma unroll
;         for (int a = 0; a < 2; ++a)
; #pragma unroll
;             for (int b = 0; b < 2; ++b)
; #pragma unroll
;                 for (int m = 0; m < 4; ++m)
; #pragma unroll
;                     for (int n = 0; n < 2; ++n) acc[a][b][m][n] = (f32x4){0.f, 0.f, 0.f, 0.f};
;         cur = nxt; cA = nA; cB = nB; ++ui;
	ds_read_b128 v[174:177], v140 offset:49152
	ds_read_b128 v[178:181], v140 offset:50176
	ds_read_b128 v[182:185], v140 offset:51200
	ds_read_b128 v[186:189], v140 offset:52224
	ds_read_b128 v[190:193], v140 offset:53248
	ds_read_b128 v[194:197], v140 offset:54272
	ds_read_b128 v[198:201], v140 offset:55296
	ds_read_b128 v[204:207], v140 offset:56320
	s_add_u32 s34, s30, 0x80
	s_addc_u32 s35, s31, 0
	s_mov_b32 m0, s48
	s_nop 0
	global_load_lds_dwordx4 v136, s[34:35]
	s_add_u32 s30, s30, 0x160080
	s_mov_b32 m0, s49
	s_nop 0
	global_load_lds_dwordx4 v138, s[34:35]
	s_addc_u32 s31, s31, 0
	s_mov_b32 m0, s52
	s_nop 0
	global_load_lds_dwordx4 v136, s[30:31]
	s_nop 0
	s_mov_b32 m0, s53
	s_nop 0
	global_load_lds_dwordx4 v138, s[30:31]
	s_mov_b32 m0, s50
	s_nop 0
	global_load_lds_dwordx4 v131, s[28:29]
	s_nop 0
	s_mov_b32 m0, s51
	s_nop 0
	global_load_lds_dwordx4 v137, s[28:29]
	s_waitcnt vmcnt(8)
	s_waitcnt lgkmcnt(0)
	s_barrier
	s_setprio 1
	v_mfma_f32_16x16x32_bf16 v[62:65], v[142:145], v[174:177], v[62:65]
	v_mfma_f32_16x16x32_bf16 v[58:61], v[150:153], v[174:177], v[58:61]
	v_mfma_f32_16x16x32_bf16 v[46:49], v[142:145], v[182:185], v[46:49]
	v_mfma_f32_16x16x32_bf16 v[42:45], v[150:153], v[182:185], v[42:45]
	s_add_i32 s60, s60, 2
	s_add_u32 s26, s26, 0x100
	s_addc_u32 s27, s27, 0
	s_cmpk_gt_u32 s60, 0x55
	v_mfma_f32_16x16x32_bf16 v[30:33], v[142:145], v[190:193], v[30:33]
	v_mfma_f32_16x16x32_bf16 v[26:29], v[150:153], v[190:193], v[26:29]
	v_mfma_f32_16x16x32_bf16 v[14:17], v[142:145], v[198:201], v[14:17]
	v_mfma_f32_16x16x32_bf16 v[10:13], v[150:153], v[198:201], v[10:13]
	v_mfma_f32_16x16x32_bf16 v[62:65], v[146:149], v[178:181], v[62:65]
	v_mfma_f32_16x16x32_bf16 v[58:61], v[154:157], v[178:181], v[58:61]
	v_mfma_f32_16x16x32_bf16 v[46:49], v[146:149], v[186:189], v[46:49]
	v_mfma_f32_16x16x32_bf16 v[42:45], v[154:157], v[186:189], v[42:45]
	v_mfma_f32_16x16x32_bf16 v[30:33], v[146:149], v[194:197], v[30:33]
	v_mfma_f32_16x16x32_bf16 v[26:29], v[154:157], v[194:197], v[26:29]
	v_mfma_f32_16x16x32_bf16 v[14:17], v[146:149], v[204:207], v[14:17]
	v_mfma_f32_16x16x32_bf16 v[10:13], v[154:157], v[204:207], v[10:13]
	v_mfma_f32_16x16x32_bf16 v[54:57], v[158:161], v[174:177], v[54:57]
	v_mfma_f32_16x16x32_bf16 v[50:53], v[166:169], v[174:177], v[50:53]
	v_mfma_f32_16x16x32_bf16 v[38:41], v[158:161], v[182:185], v[38:41]
	v_mfma_f32_16x16x32_bf16 v[34:37], v[166:169], v[182:185], v[34:37]
	v_mfma_f32_16x16x32_bf16 v[22:25], v[158:161], v[190:193], v[22:25]
	v_mfma_f32_16x16x32_bf16 v[18:21], v[166:169], v[190:193], v[18:21]
	v_mfma_f32_16x16x32_bf16 v[6:9], v[158:161], v[198:201], v[6:9]
	v_mfma_f32_16x16x32_bf16 v[2:5], v[166:169], v[198:201], v[2:5]
	v_mfma_f32_16x16x32_bf16 v[54:57], v[162:165], v[178:181], v[54:57]
	v_mfma_f32_16x16x32_bf16 v[50:53], v[170:173], v[178:181], v[50:53]
	v_mfma_f32_16x16x32_bf16 v[38:41], v[162:165], v[186:189], v[38:41]
	v_mfma_f32_16x16x32_bf16 v[34:37], v[170:173], v[186:189], v[34:37]
	v_mfma_f32_16x16x32_bf16 v[22:25], v[162:165], v[194:197], v[22:25]
	v_mfma_f32_16x16x32_bf16 v[18:21], v[170:173], v[194:197], v[18:21]
	v_mfma_f32_16x16x32_bf16 v[6:9], v[162:165], v[204:207], v[6:9]
	v_mfma_f32_16x16x32_bf16 v[2:5], v[170:173], v[204:207], v[2:5]
	s_setprio 0
	s_barrier
	s_cbranch_scc0 .LBB0_2172
	s_and_b64 vcc, exec, s[10:11]
	s_cbranch_vccnz .LBB0_2160
	v_mov_b32_e32 v2, 0
	s_mov_b32 s45, s57
	s_mov_b32 s17, s58
	s_mov_b64 s[20:21], s[24:25]
	s_mov_b64 s[22:23], s[12:13]
	s_mov_b32 s56, s59
	v_mov_b32_e32 v3, v2
	v_mov_b64_e32 v[4:5], 0
	v_mov_b64_e32 v[6:7], 0
	v_mov_b64_e32 v[8:9], 0
	v_mov_b64_e32 v[10:11], 0
	v_mov_b64_e32 v[12:13], 0
	v_mov_b64_e32 v[14:15], 0
	v_mov_b64_e32 v[16:17], 0
	v_mov_b64_e32 v[18:19], 0
	v_mov_b64_e32 v[20:21], 0
	v_mov_b64_e32 v[22:23], 0
	v_mov_b64_e32 v[24:25], 0
	v_mov_b64_e32 v[26:27], 0
	v_mov_b64_e32 v[28:29], 0
	v_mov_b64_e32 v[30:31], 0
	v_mov_b64_e32 v[32:33], 0
	v_mov_b64_e32 v[34:35], 0
	v_mov_b64_e32 v[36:37], 0
	v_mov_b64_e32 v[38:39], 0
	v_mov_b64_e32 v[40:41], 0
	v_mov_b64_e32 v[42:43], 0
	v_mov_b64_e32 v[44:45], 0
	v_mov_b64_e32 v[46:47], 0
	v_mov_b64_e32 v[48:49], 0
	v_mov_b64_e32 v[50:51], 0
	v_mov_b64_e32 v[52:53], 0
	v_mov_b64_e32 v[54:55], 0
	v_mov_b64_e32 v[56:57], 0
	v_mov_b64_e32 v[58:59], 0
	v_mov_b64_e32 v[60:61], 0
	v_mov_b64_e32 v[62:63], 0
	v_mov_b64_e32 v[64:65], 0
	v_mov_b64_e32 v[66:67], 0
	v_mov_b64_e32 v[68:69], 0
	v_mov_b64_e32 v[70:71], 0
	v_mov_b64_e32 v[72:73], 0
	v_mov_b64_e32 v[74:75], 0
	v_mov_b64_e32 v[76:77], 0
	v_mov_b64_e32 v[78:79], 0
	v_mov_b64_e32 v[80:81], 0
	v_mov_b64_e32 v[82:83], 0
	v_mov_b64_e32 v[84:85], 0
	v_mov_b64_e32 v[86:87], 0
	v_mov_b64_e32 v[88:89], 0
	v_mov_b64_e32 v[90:91], 0
	v_mov_b64_e32 v[92:93], 0
	v_mov_b64_e32 v[94:95], 0
	v_mov_b64_e32 v[96:97], 0
	v_mov_b64_e32 v[98:99], 0
	v_mov_b64_e32 v[100:101], 0
	v_mov_b64_e32 v[102:103], 0
	v_mov_b64_e32 v[104:105], 0
	v_mov_b64_e32 v[106:107], 0
	v_mov_b64_e32 v[108:109], 0
	v_mov_b64_e32 v[110:111], 0
	v_mov_b64_e32 v[112:113], 0
	v_mov_b64_e32 v[114:115], 0
	v_mov_b64_e32 v[116:117], 0
	v_mov_b64_e32 v[118:119], 0
	v_mov_b64_e32 v[120:121], 0
	v_mov_b64_e32 v[122:123], 0
	v_mov_b64_e32 v[124:125], 0
	v_mov_b64_e32 v[126:127], 0
	v_mov_b64_e32 v[128:129], 0
	s_branch .LBB0_2160
